# norm_rows loop (one of three copies): shift/scale vectors loaded once per iteration at loop top instead of 16 serialized load-wait round trips
# speedup vs baseline: 1.0072x; 1.0072x over previous
; __device__ __forceinline__ unsigned pk2(float lo, float hi) { return pg8::pk_bf16_rne(lo, hi); }
; __device__ __forceinline__ float wave_sum(float v) { v = row16_allsum(v); v = rows_pair_sum(v); v = halves_pair_sum(v); return v; }
; __device__ __forceinline__ void norm_rows(const Params& P, const float* src, float* copy_dst, int l, int shi, int gw, int NGW, int lane) {
;     ...
;     for (int m0 = 2 * gw; m0 < T; m0 += 2 * NGW) {
;         f32x4 v[2][4]; float s[2] = {0.f, 0.f};
; #pragma unroll
;         for (int q = 0; q < 2; ++q) { const f32x4* xr = (const f32x4*)(src + (size_t)(m0 + q) * D) + lane;
; #pragma unroll
;             for (int j = 0; j < 4; ++j) v[q][j] = xr[64 * j]; }
; #pragma unroll
;         for (int q = 0; q < 2; ++q) {
; #pragma unroll
;             for (int j = 0; j < 4; ++j) s[q] += (v[q][j].x * v[q][j].x + v[q][j].y * v[q][j].y) + (v[q][j].z * v[q][j].z + v[q][j].w * v[q][j].w); }
; #pragma unroll
;         for (int q = 0; q < 2; ++q) {
;             const int m = m0 + q, b = m >> 12;
;             const float rstd = 1.0f / sqrtf(wave_sum(s[q]) * (1.0f / D) + 1e-6f);
;             const f32x4* sh = (const f32x4*)(modl + (size_t)b * 9216 + shi * 1024) + lane;
;             const f32x4* sc = (const f32x4*)(modl + (size_t)b * 9216 + (shi + 1) * 1024) + lane;
;             u32x2* o8 = (u32x2*)(H + (size_t)m * D) + lane;
; #pragma unroll
;             for (int j = 0; j < 4; ++j) { const f32x4 a = sh[64 * j], c = sc[64 * j]; const f32x4 o = v[q][j] * rstd * (c + 1.0f) + a;
;                 u32x2 w; w.x = pk2(o.x, o.y); w.y = pk2(o.z, o.w); o8[64 * j] = w; }
.LBB0_52:
	v_ashrrev_i32_e32 v54, 12, v36
	v_mul_hi_i32_i24_e32 v55, 0x9000, v54
	v_mul_i32_i24_e32 v54, 0x9000, v54
	v_lshl_add_u64 v[54:55], s[10:11], 0, v[54:55]
	v_lshl_add_u64 v[56:57], v[54:55], 0, v[152:153]
	v_lshl_add_u64 v[58:59], v[56:57], 0, s[26:27]
	global_load_dwordx4 v[60:63], v[56:57], off
	global_load_dwordx4 v[64:67], v[56:57], off offset:1024
	global_load_dwordx4 v[68:71], v[56:57], off offset:2048
	global_load_dwordx4 v[72:75], v[56:57], off offset:3072
	global_load_dwordx4 v[76:79], v[58:59], off
	global_load_dwordx4 v[80:83], v[58:59], off offset:1024
	global_load_dwordx4 v[84:87], v[58:59], off offset:2048
	global_load_dwordx4 v[88:91], v[58:59], off offset:3072
	global_load_dwordx4 v[28:31], v[40:41], off offset:-4096
	global_load_dwordx4 v[24:27], v[40:41], off offset:-3072
	global_load_dwordx4 v[20:23], v[40:41], off offset:-2048
	global_load_dwordx4 v[16:19], v[40:41], off offset:-1024
	global_load_dwordx4 v[12:15], v[40:41], off
	global_load_dwordx4 v[8:11], v[40:41], off offset:1024
	global_load_dwordx4 v[4:7], v[40:41], off offset:2048
	global_load_dwordx4 v[0:3], v[40:41], off offset:3072
	v_lshl_add_u64 v[40:41], v[40:41], 0, s[20:21]
	s_waitcnt vmcnt(7)
	v_mul_f32_e32 v32, v29, v29
	v_mul_f32_e32 v33, v31, v31
	v_fmac_f32_e32 v32, v28, v28
	v_fmac_f32_e32 v33, v30, v30
	v_add_f32_e32 v32, v32, v33
	s_waitcnt vmcnt(6)
	v_mul_f32_e32 v33, v25, v25
	v_mul_f32_e32 v34, v27, v27
	v_fmac_f32_e32 v33, v24, v24
	v_fmac_f32_e32 v34, v26, v26
	v_add_f32_e32 v33, v33, v34
	v_add_f32_e32 v32, v32, v33
	s_waitcnt vmcnt(5)
	v_mul_f32_e32 v33, v21, v21
	v_mul_f32_e32 v34, v23, v23
	v_fmac_f32_e32 v33, v20, v20
	v_fmac_f32_e32 v34, v22, v22
	v_add_f32_e32 v33, v33, v34
	v_add_f32_e32 v32, v32, v33
	s_waitcnt vmcnt(4)
	v_mul_f32_e32 v33, v17, v17
	v_mul_f32_e32 v34, v19, v19
	v_fmac_f32_e32 v33, v16, v16
	v_fmac_f32_e32 v34, v18, v18
	v_add_f32_e32 v33, v33, v34
	v_add_f32_e32 v34, v32, v33
	s_waitcnt vmcnt(3)
	v_mul_f32_e32 v32, v13, v13
	v_mul_f32_e32 v33, v15, v15
	v_fmac_f32_e32 v32, v12, v12
	v_fmac_f32_e32 v33, v14, v14
	v_add_f32_e32 v32, v32, v33
	s_waitcnt vmcnt(2)
	v_mul_f32_e32 v33, v9, v9
	v_mul_f32_e32 v35, v11, v11
	v_fmac_f32_e32 v33, v8, v8
	v_fmac_f32_e32 v35, v10, v10
	v_add_f32_e32 v33, v33, v35
	v_add_f32_e32 v32, v32, v33
	s_waitcnt vmcnt(1)
	v_mul_f32_e32 v33, v5, v5
	v_mul_f32_e32 v35, v7, v7
	v_fmac_f32_e32 v33, v4, v4
	v_fmac_f32_e32 v35, v6, v6
	v_add_f32_e32 v33, v33, v35
	v_add_f32_e32 v32, v32, v33
	s_waitcnt vmcnt(0)
	v_mul_f32_e32 v33, v1, v1
	v_mul_f32_e32 v35, v3, v3
	v_fmac_f32_e32 v33, v0, v0
	v_fmac_f32_e32 v35, v2, v2
	v_add_f32_e32 v33, v33, v35
	v_add_f32_e32 v37, v32, v33
	v_ashrrev_i32_e32 v32, 12, v36
	v_mul_hi_i32_i24_e32 v33, 0x9000, v32
	v_mul_i32_i24_e32 v32, 0x9000, v32
	v_lshl_add_u64 v[32:33], s[10:11], 0, v[32:33]
	v_lshl_add_u64 v[44:45], v[32:33], 0, v[152:153]
	v_lshl_add_u64 v[42:43], v[44:45], 0, s[26:27]
	v_add_f32_dpp v32, v34, v34 row_ror:8 row_mask:0xf bank_mask:0xf bound_ctrl:1
	v_add_u32_e32 v36, s18, v36
	s_nop 0
	v_add_f32_dpp v32, v32, v32 row_ror:4 row_mask:0xf bank_mask:0xf bound_ctrl:1
	s_nop 1
	v_add_f32_dpp v32, v32, v32 row_ror:2 row_mask:0xf bank_mask:0xf bound_ctrl:1
	s_nop 1
	v_add_f32_dpp v32, v32, v32 row_ror:1 row_mask:0xf bank_mask:0xf bound_ctrl:1
	v_mov_b32_e32 v33, v32
	s_nop 1
	v_permlane16_swap_b32_e32 v32, v33
	v_add_f32_e32 v32, v32, v33
	v_mov_b32_e32 v33, v32
	s_nop 1
	v_permlane32_swap_b32_e32 v32, v33
	v_add_f32_e32 v32, v32, v33
	v_fmamk_f32 v32, v32, 0x3a800000, v155
	v_cmp_gt_f32_e32 vcc, s43, v32
	v_mul_f32_e32 v33, 0x4f800000, v32
	s_nop 0
	v_cndmask_b32_e32 v32, v32, v33, vcc
	v_sqrt_f32_e32 v33, v32
	s_nop 0
	v_add_u32_e32 v34, -1, v33
	v_fma_f32 v35, -v34, v33, v32
	v_cmp_ge_f32_e64 s[4:5], 0, v35
	v_add_u32_e32 v35, 1, v33
	s_nop 0
	v_cndmask_b32_e64 v34, v33, v34, s[4:5]
	v_fma_f32 v33, -v35, v33, v32
	v_cmp_lt_f32_e64 s[4:5], 0, v33
	s_nop 1
	v_cndmask_b32_e64 v33, v34, v35, s[4:5]
	v_mul_f32_e32 v34, 0x37800000, v33
	v_cndmask_b32_e32 v33, v33, v34, vcc
	v_cmp_class_f32_e32 vcc, v32, v175
	s_nop 1
	v_cndmask_b32_e32 v32, v33, v32, vcc
	v_div_scale_f32 v33, s[4:5], v32, v32, 1.0
	v_rcp_f32_e32 v34, v33
	s_nop 0
	v_fma_f32 v35, -v33, v34, 1.0
	v_fmac_f32_e32 v34, v35, v34
	v_div_scale_f32 v35, vcc, 1.0, v32, 1.0
	v_mul_f32_e32 v46, v35, v34
	v_fma_f32 v47, -v33, v46, v35
	v_fmac_f32_e32 v46, v47, v34
	v_fma_f32 v33, -v33, v46, v35
	v_div_fmas_f32 v33, v33, v34, v46
	v_add_co_u32_e32 v46, vcc, s36, v44
	v_div_fixup_f32 v48, v33, v32, 1.0
	s_nop 0
	v_addc_co_u32_e32 v47, vcc, 0, v45, vcc
	v_mov_b64_e32 v[32:33], v[60:61]
	v_mov_b64_e32 v[34:35], v[62:63]
	v_mov_b64_e32 v[50:51], v[76:77]
	v_mov_b64_e32 v[52:53], v[78:79]
	v_pk_mul_f32 v[28:29], v[28:29], v[48:49] op_sel_hi:[1,0]
	v_pk_mul_f32 v[30:31], v[30:31], v[48:49] op_sel_hi:[1,0]
	v_pk_mul_f32 v[24:25], v[24:25], v[48:49] op_sel_hi:[1,0]
	v_pk_mul_f32 v[26:27], v[26:27], v[48:49] op_sel_hi:[1,0]
	v_pk_mul_f32 v[20:21], v[20:21], v[48:49] op_sel_hi:[1,0]
	v_pk_mul_f32 v[22:23], v[22:23], v[48:49] op_sel_hi:[1,0]
	v_pk_mul_f32 v[16:17], v[16:17], v[48:49] op_sel_hi:[1,0]
	v_pk_mul_f32 v[18:19], v[18:19], v[48:49] op_sel_hi:[1,0]
	v_pk_add_f32 v[52:53], v[52:53], 1.0 op_sel_hi:[1,0]
	v_pk_add_f32 v[50:51], v[50:51], 1.0 op_sel_hi:[1,0]
	v_pk_fma_f32 v[30:31], v[52:53], v[30:31], v[34:35]
	v_pk_fma_f32 v[28:29], v[50:51], v[28:29], v[32:33]
	s_nop 0
	v_cvt_pk_bf16_f32 v28, v28, v29
	v_cvt_pk_bf16_f32 v29, v30, v31
	global_store_dwordx2 v[38:39], v[28:29], off offset:-3584
	s_nop 1
; __device__ __forceinline__ unsigned pk2(float lo, float hi) { return pg8::pk_bf16_rne(lo, hi); }
; __device__ __forceinline__ float wave_sum(float v) { v = row16_allsum(v); v = rows_pair_sum(v); v = halves_pair_sum(v); return v; }
; __device__ __forceinline__ void norm_rows(const Params& P, const float* src, float* copy_dst, int l, int shi, int gw, int NGW, int lane) {
;     ...
;             for (int j = 0; j < 4; ++j) s[q] += (v[q][j].x * v[q][j].x + v[q][j].y * v[q][j].y) + (v[q][j].z * v[q][j].z + v[q][j].w * v[q][j].w); }
; #pragma unroll
;         for (int q = 0; q < 2; ++q) {
;             const int m = m0 + q, b = m >> 12;
;             const float rstd = 1.0f / sqrtf(wave_sum(s[q]) * (1.0f / D) + 1e-6f);
;             const f32x4* sh = (const f32x4*)(modl + (size_t)b * 9216 + shi * 1024) + lane;
;             const f32x4* sc = (const f32x4*)(modl + (size_t)b * 9216 + (shi + 1) * 1024) + lane;
;             u32x2* o8 = (u32x2*)(H + (size_t)m * D) + lane;
; #pragma unroll
;             for (int j = 0; j < 4; ++j) { const f32x4 a = sh[64 * j], c = sc[64 * j]; const f32x4 o = v[q][j] * rstd * (c + 1.0f) + a;
;                 u32x2 w; w.x = pk2(o.x, o.y); w.y = pk2(o.z, o.w); o8[64 * j] = w; }
	v_mov_b64_e32 v[28:29], v[64:65]
	v_mov_b64_e32 v[30:31], v[66:67]
	s_nop 0
	v_mov_b64_e32 v[32:33], v[80:81]
	v_mov_b64_e32 v[34:35], v[82:83]
	v_pk_add_f32 v[34:35], v[34:35], 1.0 op_sel_hi:[1,0]
	v_pk_add_f32 v[32:33], v[32:33], 1.0 op_sel_hi:[1,0]
	v_pk_fma_f32 v[26:27], v[34:35], v[26:27], v[30:31]
	v_pk_fma_f32 v[24:25], v[32:33], v[24:25], v[28:29]
	s_nop 0
	v_cvt_pk_bf16_f32 v24, v24, v25
	v_cvt_pk_bf16_f32 v25, v26, v27
	global_store_dwordx2 v[38:39], v[24:25], off offset:-3072
	s_nop 1
	v_mov_b64_e32 v[24:25], v[68:69]
	v_mov_b64_e32 v[26:27], v[70:71]
	s_nop 0
	v_mov_b64_e32 v[28:29], v[84:85]
	v_mov_b64_e32 v[30:31], v[86:87]
	v_pk_add_f32 v[30:31], v[30:31], 1.0 op_sel_hi:[1,0]
	v_pk_add_f32 v[28:29], v[28:29], 1.0 op_sel_hi:[1,0]
	v_pk_fma_f32 v[22:23], v[30:31], v[22:23], v[26:27]
	v_pk_fma_f32 v[20:21], v[28:29], v[20:21], v[24:25]
	s_nop 0
	v_cvt_pk_bf16_f32 v20, v20, v21
	v_cvt_pk_bf16_f32 v21, v22, v23
	global_store_dwordx2 v[38:39], v[20:21], off offset:-2560
	s_nop 1
	v_mov_b64_e32 v[20:21], v[72:73]
	v_mov_b64_e32 v[22:23], v[74:75]
	s_nop 0
	v_mov_b64_e32 v[24:25], v[88:89]
	v_mov_b64_e32 v[26:27], v[90:91]
	v_pk_add_f32 v[26:27], v[26:27], 1.0 op_sel_hi:[1,0]
	v_pk_add_f32 v[24:25], v[24:25], 1.0 op_sel_hi:[1,0]
	v_pk_fma_f32 v[18:19], v[18:19], v[26:27], v[22:23]
	v_pk_fma_f32 v[16:17], v[16:17], v[24:25], v[20:21]
	s_nop 0
	v_cvt_pk_bf16_f32 v16, v16, v17
	v_cvt_pk_bf16_f32 v17, v18, v19
	global_store_dwordx2 v[38:39], v[16:17], off offset:-2048
	v_add_f32_dpp v16, v37, v37 row_ror:8 row_mask:0xf bank_mask:0xf bound_ctrl:1
	s_nop 1
	v_add_f32_dpp v16, v16, v16 row_ror:4 row_mask:0xf bank_mask:0xf bound_ctrl:1
	s_nop 1
	v_add_f32_dpp v16, v16, v16 row_ror:2 row_mask:0xf bank_mask:0xf bound_ctrl:1
	s_nop 1
	v_add_f32_dpp v16, v16, v16 row_ror:1 row_mask:0xf bank_mask:0xf bound_ctrl:1
	v_mov_b32_e32 v17, v16
	s_nop 1
	v_permlane16_swap_b32_e32 v16, v17
	v_add_f32_e32 v16, v16, v17
	v_mov_b32_e32 v17, v16
	s_nop 1
	v_permlane32_swap_b32_e32 v16, v17
	v_add_f32_e32 v16, v16, v17
	v_fmamk_f32 v16, v16, 0x3a800000, v155
	v_cmp_gt_f32_e32 vcc, s43, v16
	v_mul_f32_e32 v17, 0x4f800000, v16
	s_nop 0
	v_cndmask_b32_e32 v16, v16, v17, vcc
	v_sqrt_f32_e32 v17, v16
	s_nop 0
	v_add_u32_e32 v18, -1, v17
	v_fma_f32 v19, -v18, v17, v16
	v_cmp_ge_f32_e64 s[4:5], 0, v19
	v_add_u32_e32 v19, 1, v17
	s_nop 0
	v_cndmask_b32_e64 v18, v17, v18, s[4:5]
	v_fma_f32 v17, -v19, v17, v16
	v_cmp_lt_f32_e64 s[4:5], 0, v17
	s_nop 1
	v_cndmask_b32_e64 v17, v18, v19, s[4:5]
	v_mul_f32_e32 v18, 0x37800000, v17
	v_cndmask_b32_e32 v17, v17, v18, vcc
	v_cmp_class_f32_e32 vcc, v16, v175
	s_nop 1
	v_cndmask_b32_e32 v16, v17, v16, vcc
	v_div_scale_f32 v17, s[4:5], v16, v16, 1.0
	v_rcp_f32_e32 v18, v17
	s_nop 0
	v_fma_f32 v19, -v17, v18, 1.0
	v_fmac_f32_e32 v18, v19, v18
	v_div_scale_f32 v19, vcc, 1.0, v16, 1.0
	v_mul_f32_e32 v20, v19, v18
	v_fma_f32 v21, -v17, v20, v19
	v_fmac_f32_e32 v20, v21, v18
	v_fma_f32 v17, -v17, v20, v19
	v_div_fmas_f32 v17, v17, v18, v20
	v_div_fixup_f32 v20, v17, v16, 1.0
	v_mov_b64_e32 v[16:17], v[60:61]
	v_mov_b64_e32 v[18:19], v[62:63]
	v_mov_b64_e32 v[22:23], v[76:77]
	v_mov_b64_e32 v[24:25], v[78:79]
	v_pk_mul_f32 v[12:13], v[12:13], v[20:21] op_sel_hi:[1,0]
	v_pk_mul_f32 v[14:15], v[14:15], v[20:21] op_sel_hi:[1,0]
	v_pk_mul_f32 v[8:9], v[8:9], v[20:21] op_sel_hi:[1,0]
	v_pk_mul_f32 v[10:11], v[10:11], v[20:21] op_sel_hi:[1,0]
	v_pk_mul_f32 v[4:5], v[4:5], v[20:21] op_sel_hi:[1,0]
	v_pk_mul_f32 v[6:7], v[6:7], v[20:21] op_sel_hi:[1,0]
	v_pk_mul_f32 v[0:1], v[0:1], v[20:21] op_sel_hi:[1,0]
	v_pk_mul_f32 v[2:3], v[2:3], v[20:21] op_sel_hi:[1,0]
	v_cmp_lt_i32_e32 vcc, s45, v36
	s_or_b64 s[12:13], vcc, s[12:13]
	v_pk_add_f32 v[24:25], v[24:25], 1.0 op_sel_hi:[1,0]
	v_pk_add_f32 v[22:23], v[22:23], 1.0 op_sel_hi:[1,0]
	v_pk_fma_f32 v[14:15], v[24:25], v[14:15], v[18:19]
	v_pk_fma_f32 v[12:13], v[22:23], v[12:13], v[16:17]
	s_nop 0
	v_cvt_pk_bf16_f32 v12, v12, v13
	v_cvt_pk_bf16_f32 v13, v14, v15
	global_store_dwordx2 v[38:39], v[12:13], off offset:-1536
	s_nop 1
	v_mov_b64_e32 v[12:13], v[64:65]
	v_mov_b64_e32 v[14:15], v[66:67]
	s_nop 0
	v_mov_b64_e32 v[16:17], v[80:81]
	v_mov_b64_e32 v[18:19], v[82:83]
	v_pk_add_f32 v[18:19], v[18:19], 1.0 op_sel_hi:[1,0]
	v_pk_add_f32 v[16:17], v[16:17], 1.0 op_sel_hi:[1,0]
	v_pk_fma_f32 v[10:11], v[18:19], v[10:11], v[14:15]
	v_pk_fma_f32 v[8:9], v[16:17], v[8:9], v[12:13]
	s_nop 0
	v_cvt_pk_bf16_f32 v8, v8, v9
	v_cvt_pk_bf16_f32 v9, v10, v11
	global_store_dwordx2 v[38:39], v[8:9], off offset:-1024
	s_nop 1
	v_mov_b64_e32 v[8:9], v[68:69]
	v_mov_b64_e32 v[10:11], v[70:71]
	s_nop 0
	v_mov_b64_e32 v[12:13], v[84:85]
	v_mov_b64_e32 v[14:15], v[86:87]
	v_pk_add_f32 v[14:15], v[14:15], 1.0 op_sel_hi:[1,0]
	v_pk_add_f32 v[12:13], v[12:13], 1.0 op_sel_hi:[1,0]
	v_pk_fma_f32 v[6:7], v[14:15], v[6:7], v[10:11]
	v_pk_fma_f32 v[4:5], v[12:13], v[4:5], v[8:9]
	s_nop 0
	v_cvt_pk_bf16_f32 v4, v4, v5
	v_cvt_pk_bf16_f32 v5, v6, v7
	global_store_dwordx2 v[38:39], v[4:5], off offset:-512
	s_nop 1
	v_mov_b64_e32 v[4:5], v[72:73]
	v_mov_b64_e32 v[6:7], v[74:75]
	s_nop 0
	v_mov_b64_e32 v[8:9], v[88:89]
	v_mov_b64_e32 v[10:11], v[90:91]
	v_pk_add_f32 v[10:11], v[10:11], 1.0 op_sel_hi:[1,0]
	v_pk_add_f32 v[8:9], v[8:9], 1.0 op_sel_hi:[1,0]
	v_pk_fma_f32 v[2:3], v[2:3], v[10:11], v[6:7]
	v_pk_fma_f32 v[0:1], v[0:1], v[8:9], v[4:5]
	s_nop 0
	v_cvt_pk_bf16_f32 v0, v0, v1
	v_cvt_pk_bf16_f32 v1, v2, v3
	global_store_dwordx2 v[38:39], v[0:1], off
	v_lshl_add_u64 v[38:39], v[38:39], 0, s[24:25]
	s_andn2_b64 exec, exec, s[12:13]
	s_cbranch_execnz .LBB0_52
